# v34 plus: in the K=2816 fused epilogue three of the four second-half residual load pairs are issued as soon as an earlier row group frees registers (copied into place after the existing wait)
# speedup vs baseline: 1.0009x; 1.0009x over previous
.LBB0_510:
	s_or_b64 exec, exec, s[0:1]
	v_add_u32_e32 v168, s26, v215
	v_ashrrev_i32_e32 v169, 31, v168
	v_lshlrev_b64 v[168:169], 11, v[168:169]
	v_lshl_add_u64 v[168:169], v[192:193], 0, v[168:169]
	global_load_dwordx4 v[172:175], v[168:169], off offset:256
	global_load_dwordx4 v[168:171], v[168:169], off
	v_lshl_add_u32 v120, v216, 2, s63
	ds_read_b32 v122, v120
	v_cvt_f32_f16_sdwa v133, v164 dst_sel:DWORD dst_unused:UNUSED_PAD src0_sel:WORD_1
	v_cvt_f32_f16_e32 v132, v164
	v_cvt_f32_f16_sdwa v135, v165 dst_sel:DWORD dst_unused:UNUSED_PAD src0_sel:WORD_1
	v_cvt_f32_f16_e32 v134, v165
	v_cvt_f32_f16_sdwa v137, v166 dst_sel:DWORD dst_unused:UNUSED_PAD src0_sel:WORD_1
	v_cvt_f32_f16_e32 v136, v166
	v_cvt_f32_f16_sdwa v139, v167 dst_sel:DWORD dst_unused:UNUSED_PAD src0_sel:WORD_1
	v_cvt_f32_f16_e32 v138, v167
	v_cvt_f32_f16_sdwa v141, v160 dst_sel:DWORD dst_unused:UNUSED_PAD src0_sel:WORD_1
	v_cvt_f32_f16_e32 v140, v160
	v_cvt_f32_f16_sdwa v143, v161 dst_sel:DWORD dst_unused:UNUSED_PAD src0_sel:WORD_1
	v_cvt_f32_f16_e32 v142, v161
	v_cvt_f32_f16_sdwa v161, v162 dst_sel:DWORD dst_unused:UNUSED_PAD src0_sel:WORD_1
	v_cvt_f32_f16_e32 v160, v162
	v_cvt_f32_f16_sdwa v165, v163 dst_sel:DWORD dst_unused:UNUSED_PAD src0_sel:WORD_1
	v_cvt_f32_f16_e32 v164, v163
	v_add_u32_e32 v120, s26, v216
	s_waitcnt lgkmcnt(0)
	v_ashrrev_i32_e32 v121, 31, v120
	v_pk_mul_f32 v[110:111], v[110:111], v[122:123] op_sel_hi:[1,0]
	v_pk_mul_f32 v[108:109], v[108:109], v[122:123] op_sel_hi:[1,0]
	v_pk_mul_f32 v[106:107], v[106:107], v[122:123] op_sel_hi:[1,0]
	v_pk_mul_f32 v[104:105], v[104:105], v[122:123] op_sel_hi:[1,0]
	v_pk_mul_f32 v[102:103], v[102:103], v[122:123] op_sel_hi:[1,0]
	v_pk_mul_f32 v[100:101], v[100:101], v[122:123] op_sel_hi:[1,0]
	v_pk_mul_f32 v[98:99], v[98:99], v[122:123] op_sel_hi:[1,0]
	v_pk_mul_f32 v[96:97], v[96:97], v[122:123] op_sel_hi:[1,0]
	v_lshlrev_b64 v[120:121], 10, v[120:121]
	v_pk_fma_f32 v[110:111], v[130:131], v[110:111], v[134:135]
	v_pk_fma_f32 v[108:109], v[128:129], v[108:109], v[132:133]
	v_pk_fma_f32 v[106:107], v[126:127], v[106:107], v[138:139]
	v_pk_fma_f32 v[104:105], v[124:125], v[104:105], v[136:137]
	v_pk_fma_f32 v[102:103], v[118:119], v[102:103], v[142:143]
	v_pk_fma_f32 v[100:101], v[116:117], v[100:101], v[140:141]
	v_pk_fma_f32 v[98:99], v[114:115], v[98:99], v[164:165]
	s_and_b64 vcc, exec, s[10:11]
	v_pk_fma_f32 v[96:97], v[112:113], v[96:97], v[160:161]
	s_cbranch_vccnz .LBB0_551
	v_lshl_add_u64 v[122:123], v[120:121], 0, v[194:195]
	v_lshl_add_u64 v[122:123], v[122:123], 2, s[38:39]
	global_store_dwordx4 v[122:123], v[108:111], off
	global_store_dwordx4 v[122:123], v[104:107], off offset:16
	global_store_dwordx4 v[122:123], v[100:103], off offset:512
	global_store_dwordx4 v[122:123], v[96:99], off offset:528
	s_cbranch_execnz .LBB0_513

.LBB0_515:
	s_or_b64 exec, exec, s[0:1]
	v_add_u32_e32 v160, s26, v215
	v_or_b32_e32 v160, 16, v160
	v_ashrrev_i32_e32 v161, 31, v160
	v_lshlrev_b64 v[160:161], 11, v[160:161]
	v_lshl_add_u64 v[160:161], v[192:193], 0, v[160:161]
	global_load_dwordx4 v[164:167], v[160:161], off offset:256
	global_load_dwordx4 v[160:163], v[160:161], off
	v_lshl_add_u32 v96, v217, 2, s63
	ds_read_b32 v98, v96
	v_cvt_f32_f16_sdwa v101, v156 dst_sel:DWORD dst_unused:UNUSED_PAD src0_sel:WORD_1
	v_cvt_f32_f16_e32 v100, v156
	v_cvt_f32_f16_sdwa v103, v157 dst_sel:DWORD dst_unused:UNUSED_PAD src0_sel:WORD_1
	v_cvt_f32_f16_e32 v102, v157
	v_cvt_f32_f16_sdwa v105, v158 dst_sel:DWORD dst_unused:UNUSED_PAD src0_sel:WORD_1
	v_cvt_f32_f16_e32 v104, v158
	v_cvt_f32_f16_sdwa v107, v159 dst_sel:DWORD dst_unused:UNUSED_PAD src0_sel:WORD_1
	v_cvt_f32_f16_e32 v106, v159
	v_cvt_f32_f16_sdwa v109, v152 dst_sel:DWORD dst_unused:UNUSED_PAD src0_sel:WORD_1
	v_cvt_f32_f16_e32 v108, v152
	v_cvt_f32_f16_sdwa v111, v153 dst_sel:DWORD dst_unused:UNUSED_PAD src0_sel:WORD_1
	v_cvt_f32_f16_e32 v110, v153
	v_cvt_f32_f16_sdwa v121, v154 dst_sel:DWORD dst_unused:UNUSED_PAD src0_sel:WORD_1
	v_cvt_f32_f16_e32 v120, v154
	v_cvt_f32_f16_sdwa v123, v155 dst_sel:DWORD dst_unused:UNUSED_PAD src0_sel:WORD_1
	v_cvt_f32_f16_e32 v122, v155
	v_add_u32_e32 v96, s26, v217
	s_waitcnt lgkmcnt(0)
	v_ashrrev_i32_e32 v97, 31, v96
	v_pk_mul_f32 v[94:95], v[94:95], v[98:99] op_sel_hi:[1,0]
	v_pk_mul_f32 v[92:93], v[92:93], v[98:99] op_sel_hi:[1,0]
	v_pk_mul_f32 v[90:91], v[90:91], v[98:99] op_sel_hi:[1,0]
	v_pk_mul_f32 v[88:89], v[88:89], v[98:99] op_sel_hi:[1,0]
	v_pk_mul_f32 v[86:87], v[86:87], v[98:99] op_sel_hi:[1,0]
	v_pk_mul_f32 v[84:85], v[84:85], v[98:99] op_sel_hi:[1,0]
	v_pk_mul_f32 v[82:83], v[82:83], v[98:99] op_sel_hi:[1,0]
	v_pk_mul_f32 v[80:81], v[80:81], v[98:99] op_sel_hi:[1,0]
	v_lshlrev_b64 v[96:97], 10, v[96:97]
	v_pk_fma_f32 v[94:95], v[130:131], v[94:95], v[102:103]
	v_pk_fma_f32 v[92:93], v[128:129], v[92:93], v[100:101]
	v_pk_fma_f32 v[90:91], v[126:127], v[90:91], v[106:107]
	v_pk_fma_f32 v[88:89], v[124:125], v[88:89], v[104:105]
	v_pk_fma_f32 v[86:87], v[118:119], v[86:87], v[110:111]
	v_pk_fma_f32 v[84:85], v[116:117], v[84:85], v[108:109]
	v_pk_fma_f32 v[82:83], v[114:115], v[82:83], v[122:123]
	s_and_b64 vcc, exec, s[10:11]
	v_pk_fma_f32 v[80:81], v[112:113], v[80:81], v[120:121]
	s_cbranch_vccnz .LBB0_552
	v_lshl_add_u64 v[98:99], v[96:97], 0, v[194:195]
	v_lshl_add_u64 v[98:99], v[98:99], 2, s[38:39]
	global_store_dwordx4 v[98:99], v[92:95], off
	global_store_dwordx4 v[98:99], v[88:91], off offset:16
	global_store_dwordx4 v[98:99], v[84:87], off offset:512
	global_store_dwordx4 v[98:99], v[80:83], off offset:528
	s_cbranch_execnz .LBB0_518

.LBB0_520:
	s_or_b64 exec, exec, s[0:1]
	v_add_u32_e32 v152, s26, v215
	v_or_b32_e32 v152, 32, v152
	v_ashrrev_i32_e32 v153, 31, v152
	v_lshlrev_b64 v[152:153], 11, v[152:153]
	v_lshl_add_u64 v[152:153], v[192:193], 0, v[152:153]
	global_load_dwordx4 v[156:159], v[152:153], off offset:256
	global_load_dwordx4 v[152:155], v[152:153], off
	v_lshl_add_u32 v80, v218, 2, s63
	ds_read_b32 v82, v80
	v_cvt_f32_f16_sdwa v85, v148 dst_sel:DWORD dst_unused:UNUSED_PAD src0_sel:WORD_1
	v_cvt_f32_f16_e32 v84, v148
	v_cvt_f32_f16_sdwa v87, v149 dst_sel:DWORD dst_unused:UNUSED_PAD src0_sel:WORD_1
	v_cvt_f32_f16_e32 v86, v149
	v_cvt_f32_f16_sdwa v89, v150 dst_sel:DWORD dst_unused:UNUSED_PAD src0_sel:WORD_1
	v_cvt_f32_f16_e32 v88, v150
	v_cvt_f32_f16_sdwa v91, v151 dst_sel:DWORD dst_unused:UNUSED_PAD src0_sel:WORD_1
	v_cvt_f32_f16_e32 v90, v151
	v_cvt_f32_f16_sdwa v93, v144 dst_sel:DWORD dst_unused:UNUSED_PAD src0_sel:WORD_1
	v_cvt_f32_f16_e32 v92, v144
	v_cvt_f32_f16_sdwa v95, v145 dst_sel:DWORD dst_unused:UNUSED_PAD src0_sel:WORD_1
	v_cvt_f32_f16_e32 v94, v145
	v_cvt_f32_f16_sdwa v97, v146 dst_sel:DWORD dst_unused:UNUSED_PAD src0_sel:WORD_1
	v_cvt_f32_f16_e32 v96, v146
	v_cvt_f32_f16_sdwa v99, v147 dst_sel:DWORD dst_unused:UNUSED_PAD src0_sel:WORD_1
	v_cvt_f32_f16_e32 v98, v147
	v_add_u32_e32 v80, s26, v218
	s_waitcnt lgkmcnt(0)
	v_ashrrev_i32_e32 v81, 31, v80
	v_pk_mul_f32 v[78:79], v[78:79], v[82:83] op_sel_hi:[1,0]
	v_pk_mul_f32 v[76:77], v[76:77], v[82:83] op_sel_hi:[1,0]
	v_pk_mul_f32 v[74:75], v[74:75], v[82:83] op_sel_hi:[1,0]
	v_pk_mul_f32 v[72:73], v[72:73], v[82:83] op_sel_hi:[1,0]
	v_pk_mul_f32 v[70:71], v[70:71], v[82:83] op_sel_hi:[1,0]
	v_pk_mul_f32 v[68:69], v[68:69], v[82:83] op_sel_hi:[1,0]
	v_pk_mul_f32 v[66:67], v[66:67], v[82:83] op_sel_hi:[1,0]
	v_pk_mul_f32 v[64:65], v[64:65], v[82:83] op_sel_hi:[1,0]
	v_lshlrev_b64 v[80:81], 10, v[80:81]
	v_pk_fma_f32 v[78:79], v[130:131], v[78:79], v[86:87]
	v_pk_fma_f32 v[76:77], v[128:129], v[76:77], v[84:85]
	v_pk_fma_f32 v[74:75], v[126:127], v[74:75], v[90:91]
	v_pk_fma_f32 v[72:73], v[124:125], v[72:73], v[88:89]
	v_pk_fma_f32 v[70:71], v[118:119], v[70:71], v[94:95]
	v_pk_fma_f32 v[68:69], v[116:117], v[68:69], v[92:93]
	v_pk_fma_f32 v[66:67], v[114:115], v[66:67], v[98:99]
	s_and_b64 vcc, exec, s[10:11]
	v_pk_fma_f32 v[64:65], v[112:113], v[64:65], v[96:97]
	s_cbranch_vccnz .LBB0_553
	v_lshl_add_u64 v[82:83], v[80:81], 0, v[194:195]
	v_lshl_add_u64 v[82:83], v[82:83], 2, s[38:39]
	global_store_dwordx4 v[82:83], v[76:79], off
	global_store_dwordx4 v[82:83], v[72:75], off offset:16
	global_store_dwordx4 v[82:83], v[68:71], off offset:512
	global_store_dwordx4 v[82:83], v[64:67], off offset:528
	s_cbranch_execnz .LBB0_523

.LBB0_525:
	s_or_b64 exec, exec, s[0:1]
	v_add_u32_e32 v88, s26, v215
	v_ashrrev_i32_e32 v89, 31, v88
	s_waitcnt lgkmcnt(0)
	v_lshlrev_b64 v[64:65], 11, v[88:89]
	v_lshl_add_u64 v[64:65], v[192:193], 0, v[64:65]
	v_or_b32_e32 v66, 16, v88
	v_or_b32_e32 v68, 32, v88
	v_or_b32_e32 v64, 48, v88
	v_ashrrev_i32_e32 v67, 31, v66
	v_ashrrev_i32_e32 v69, 31, v68
	v_ashrrev_i32_e32 v65, 31, v64
	v_lshlrev_b64 v[66:67], 11, v[66:67]
	v_lshlrev_b64 v[68:69], 11, v[68:69]
	v_lshlrev_b64 v[64:65], 11, v[64:65]
	v_lshl_add_u64 v[66:67], v[192:193], 0, v[66:67]
	v_lshl_add_u64 v[68:69], v[192:193], 0, v[68:69]
	v_lshl_add_u64 v[64:65], v[192:193], 0, v[64:65]
	s_nop 0
	flat_load_dwordx4 v[68:71], v[64:65]
	s_nop 0
	flat_load_dwordx4 v[64:67], v[64:65] offset:256
	v_lshl_add_u32 v98, v215, 2, s63
	ds_read_b32 v98, v98
	s_and_b64 vcc, exec, s[10:11]
	v_lshlrev_b64 v[88:89], 10, v[88:89]
	s_waitcnt lgkmcnt(0)
	v_pk_mul_f32 v[62:63], v[62:63], v[98:99] op_sel_hi:[1,0]
	v_pk_mul_f32 v[60:61], v[60:61], v[98:99] op_sel_hi:[1,0]
	v_pk_mul_f32 v[58:59], v[58:59], v[98:99] op_sel_hi:[1,0]
	v_pk_mul_f32 v[56:57], v[56:57], v[98:99] op_sel_hi:[1,0]
	v_pk_mul_f32 v[54:55], v[54:55], v[98:99] op_sel_hi:[1,0]
	v_pk_mul_f32 v[52:53], v[52:53], v[98:99] op_sel_hi:[1,0]
	v_pk_mul_f32 v[50:51], v[50:51], v[98:99] op_sel_hi:[1,0]
	v_pk_mul_f32 v[48:49], v[48:49], v[98:99] op_sel_hi:[1,0]
	s_waitcnt vmcnt(0)
	v_mov_b32_e32 v90, v168
	v_mov_b32_e32 v91, v169
	v_mov_b32_e32 v92, v170
	v_mov_b32_e32 v93, v171
	v_mov_b32_e32 v94, v172
	v_mov_b32_e32 v95, v173
	v_mov_b32_e32 v96, v174
	v_mov_b32_e32 v97, v175
	v_mov_b32_e32 v84, v160
	v_mov_b32_e32 v85, v161
	v_mov_b32_e32 v86, v162
	v_mov_b32_e32 v87, v163
	v_mov_b32_e32 v80, v164
	v_mov_b32_e32 v81, v165
	v_mov_b32_e32 v82, v166
	v_mov_b32_e32 v83, v167
	v_mov_b32_e32 v76, v152
	v_mov_b32_e32 v77, v153
	v_mov_b32_e32 v78, v154
	v_mov_b32_e32 v79, v155
	v_mov_b32_e32 v72, v156
	v_mov_b32_e32 v73, v157
	v_mov_b32_e32 v74, v158
	v_mov_b32_e32 v75, v159
	v_cvt_f32_f16_e32 v98, v90
	v_cvt_f32_f16_sdwa v99, v90 dst_sel:DWORD dst_unused:UNUSED_PAD src0_sel:WORD_1
	v_cvt_f32_f16_e32 v90, v91
	v_cvt_f32_f16_sdwa v91, v91 dst_sel:DWORD dst_unused:UNUSED_PAD src0_sel:WORD_1
	v_cvt_f32_f16_e32 v100, v92
	v_cvt_f32_f16_sdwa v101, v92 dst_sel:DWORD dst_unused:UNUSED_PAD src0_sel:WORD_1
	v_cvt_f32_f16_e32 v92, v93
	v_cvt_f32_f16_sdwa v93, v93 dst_sel:DWORD dst_unused:UNUSED_PAD src0_sel:WORD_1
	v_cvt_f32_f16_e32 v102, v94
	v_cvt_f32_f16_sdwa v103, v94 dst_sel:DWORD dst_unused:UNUSED_PAD src0_sel:WORD_1
	v_cvt_f32_f16_e32 v94, v95
	v_cvt_f32_f16_sdwa v95, v95 dst_sel:DWORD dst_unused:UNUSED_PAD src0_sel:WORD_1
	v_cvt_f32_f16_e32 v104, v96
	v_cvt_f32_f16_sdwa v105, v96 dst_sel:DWORD dst_unused:UNUSED_PAD src0_sel:WORD_1
	v_cvt_f32_f16_e32 v96, v97
	v_cvt_f32_f16_sdwa v97, v97 dst_sel:DWORD dst_unused:UNUSED_PAD src0_sel:WORD_1
	v_pk_fma_f32 v[62:63], v[130:131], v[62:63], v[90:91]
	v_pk_fma_f32 v[60:61], v[128:129], v[60:61], v[98:99]
	v_pk_fma_f32 v[58:59], v[126:127], v[58:59], v[92:93]
	v_pk_fma_f32 v[56:57], v[124:125], v[56:57], v[100:101]
	v_pk_fma_f32 v[54:55], v[118:119], v[54:55], v[94:95]
	v_pk_fma_f32 v[52:53], v[116:117], v[52:53], v[102:103]
	v_pk_fma_f32 v[50:51], v[114:115], v[50:51], v[96:97]
	v_pk_fma_f32 v[48:49], v[112:113], v[48:49], v[104:105]
	s_cbranch_vccnz .LBB0_554
	v_lshl_add_u64 v[90:91], v[88:89], 0, v[194:195]
	v_lshl_add_u64 v[90:91], v[90:91], 2, s[38:39]
	global_store_dwordx4 v[90:91], v[60:63], off
	global_store_dwordx4 v[90:91], v[56:59], off offset:16
	global_store_dwordx4 v[90:91], v[52:55], off offset:512
	global_store_dwordx4 v[90:91], v[48:51], off offset:528
	s_cbranch_execnz .LBB0_528
